# previous version + F1 epilogue halo-row stores addressed by scalar bases and one 32-bit lane offset (no v_add_co/v_addc chains)
# speedup vs baseline: 1.0002x; 1.0002x over previous
; #define PG8_LAS __attribute__((address_space(3)))
;     template <bool PR = false> __device__ __forceinline__ void apply(f32x4 (&acc)[2][2][4][2], int p, int wr, int wc, int fr, int fq) const {
;     ...
;             for (int m = 0; m < 4; ++m) rs[ai][m] = __builtin_amdgcn_rsqf((float)Tr[ai * HALF + (PR ? m : m * 16)] * (1.0f / (1048576.0f * 2048.0f)) + 1e-6f);
; #pragma unroll
;         for (int bj = 0; bj < 2; ++bj)
; #pragma unroll
;             for (int n = 0; n < 2; ++n) { const f32x4 bv = *(const PG8_LAS f32x4*)(Tb + bj * HALF + 4 * n);
; #pragma unroll
;                 for (int ai = 0; ai < 2; ++ai)
; #pragma unroll
;                     for (int m = 0; m < 4; ++m) acc[ai][bj][m][n] = acc[ai][bj][m][n] * rs[ai][m] + bv; }
;     __device__ __forceinline__ void operator()(f32x4 (&acc)[2][2][4][2], const Unit& u, int p, int wr, int wc, int fr, int fq) const {
;     ...
;         if (fr == 15) {
; #pragma unroll
;             for (int ai = 0; ai < 2; ++ai)
; #pragma unroll
;                 for (int mm = 0; mm < 2; ++mm)
; #pragma unroll
;                     for (int bj = 0; bj < 2; ++bj)
; #pragma unroll
;                         for (int n = 0; n < 2; ++n) *(PG8_LAS f32x4*)(X + (((ai * 2 + wr) * 2 + mm) * 256) + bj * 128 + tcol + 4 * n) = acc[ai][bj][2 + mm][n];
;             if (wr == 1) {
; #pragma unroll
;                 for (int mm = 0; mm < 2; ++mm)
; #pragma unroll
;                     for (int bj = 0; bj < 2; ++bj)
; #pragma unroll
;                         for (int n = 0; n < 2; ++n) *(f32x4*)(HALO + ((size_t)u.pm * 4 + 2 + mm) * 11008 + bj * 5504 + ch0 + 4 * n) = acc[1][bj][2 + mm][n]; }
.LBB0_1330:
	s_and_b32 s0, s11, 1
	v_lshl_or_b32 v200, s10, 7, v204
	s_mul_i32 s10, s0, 0xc00
	s_add_i32 s10, s10, 0
	s_add_i32 s10, s10, 0x22000
	s_add_i32 s11, s10, s33
	v_add_u32_e32 v82, s11, v205
	ds_read_b128 v[150:153], v82
	ds_read_b128 v[66:69], v82 offset:16
	s_add_i32 s10, s10, s47
	v_add_u32_e32 v155, s10, v206
	s_waitcnt lgkmcnt(0)
	v_ffbh_u32_e32 v70, v67
	v_min_u32_e32 v70, 32, v70
	v_lshlrev_b64 v[66:67], v70, v[66:67]
	v_min_u32_e32 v66, 1, v66
	v_or_b32_e32 v66, v67, v66
	v_cvt_f32_u32_e32 v66, v66
	v_sub_u32_e32 v67, 32, v70
	v_ldexp_f32 v66, v66, v67
	v_fmamk_f32 v66, v66, 0x30000000, v233
	v_rsq_f32_e32 v154, v66
	v_ffbh_u32_e32 v66, v69
	v_min_u32_e32 v70, 32, v66
	v_lshlrev_b64 v[66:67], v70, v[68:69]
	v_min_u32_e32 v66, 1, v66
	v_or_b32_e32 v66, v67, v66
	v_cvt_f32_u32_e32 v66, v66
	v_sub_u32_e32 v67, 32, v70
	v_ldexp_f32 v66, v66, v67
	v_fmamk_f32 v66, v66, 0x30000000, v233
	v_rsq_f32_e32 v156, v66
	ds_read_b128 v[70:73], v82 offset:1024
	ds_read_b128 v[66:69], v82 offset:1040
	s_waitcnt lgkmcnt(0)
	v_ffbh_u32_e32 v82, v67
	v_min_u32_e32 v82, 32, v82
	v_lshlrev_b64 v[66:67], v82, v[66:67]
	v_min_u32_e32 v66, 1, v66
	v_or_b32_e32 v66, v67, v66
	v_cvt_f32_u32_e32 v66, v66
	v_sub_u32_e32 v67, 32, v82
	v_ldexp_f32 v66, v66, v67
	v_fmamk_f32 v66, v66, 0x30000000, v233
	v_rsq_f32_e32 v158, v66
	v_ffbh_u32_e32 v66, v69
	v_min_u32_e32 v82, 32, v66
	v_lshlrev_b64 v[66:67], v82, v[68:69]
	v_min_u32_e32 v66, 1, v66
	v_or_b32_e32 v66, v67, v66
	v_cvt_f32_u32_e32 v66, v66
	v_sub_u32_e32 v67, 32, v82
	v_ldexp_f32 v66, v66, v67
	v_fmamk_f32 v66, v66, 0x30000000, v233
	v_rsq_f32_e32 v160, v66
	ds_read_b128 v[82:85], v155 offset:2048
	ds_read_b128 v[66:69], v155 offset:2064
	s_waitcnt lgkmcnt(0)
	v_pk_fma_f32 v[144:145], v[80:81], v[154:155], v[84:85] op_sel_hi:[1,0,1]
	v_pk_fma_f32 v[142:143], v[78:79], v[154:155], v[82:83] op_sel_hi:[1,0,1]
	v_pk_fma_f32 v[80:81], v[60:61], v[160:161], v[84:85] op_sel_hi:[1,0,1]
	v_pk_fma_f32 v[78:79], v[58:59], v[160:161], v[82:83] op_sel_hi:[1,0,1]
	v_pk_fma_f32 v[60:61], v[56:57], v[158:159], v[68:69] op_sel_hi:[1,0,1]
	v_pk_fma_f32 v[58:59], v[54:55], v[158:159], v[66:67] op_sel_hi:[1,0,1]
	ds_read_b128 v[54:57], v155 offset:2560
	v_pk_fma_f32 v[148:149], v[76:77], v[156:157], v[84:85] op_sel_hi:[1,0,1]
	v_pk_fma_f32 v[146:147], v[74:75], v[156:157], v[82:83] op_sel_hi:[1,0,1]
	v_pk_fma_f32 v[76:77], v[64:65], v[158:159], v[84:85] op_sel_hi:[1,0,1]
	v_pk_fma_f32 v[74:75], v[62:63], v[158:159], v[82:83] op_sel_hi:[1,0,1]
	v_pk_fma_f32 v[64:65], v[52:53], v[160:161], v[68:69] op_sel_hi:[1,0,1]
	v_pk_fma_f32 v[62:63], v[50:51], v[160:161], v[66:67] op_sel_hi:[1,0,1]
	s_waitcnt lgkmcnt(0)
	v_pk_fma_f32 v[52:53], v[40:41], v[160:161], v[56:57] op_sel_hi:[1,0,1]
	v_pk_fma_f32 v[50:51], v[38:39], v[160:161], v[54:55] op_sel_hi:[1,0,1]
	ds_read_b128 v[38:41], v155 offset:2576
	v_pk_fma_f32 v[140:141], v[140:141], v[154:155], v[68:69] op_sel_hi:[1,0,1]
	v_pk_fma_f32 v[138:139], v[138:139], v[154:155], v[66:67] op_sel_hi:[1,0,1]
	v_pk_fma_f32 v[132:133], v[132:133], v[154:155], v[56:57] op_sel_hi:[1,0,1]
	v_pk_fma_f32 v[130:131], v[130:131], v[154:155], v[54:55] op_sel_hi:[1,0,1]
	s_waitcnt lgkmcnt(0)
	v_pk_fma_f32 v[124:125], v[124:125], v[154:155], v[40:41] op_sel_hi:[1,0,1]
	v_pk_fma_f32 v[122:123], v[122:123], v[154:155], v[38:39] op_sel_hi:[1,0,1]
	v_cndmask_b32_e64 v154, 0, 1, s[74:75]
	v_pk_fma_f32 v[136:137], v[136:137], v[156:157], v[68:69] op_sel_hi:[1,0,1]
	v_pk_fma_f32 v[134:135], v[134:135], v[156:157], v[66:67] op_sel_hi:[1,0,1]
	v_pk_fma_f32 v[128:129], v[128:129], v[156:157], v[56:57] op_sel_hi:[1,0,1]
	v_pk_fma_f32 v[126:127], v[126:127], v[156:157], v[54:55] op_sel_hi:[1,0,1]
	v_pk_fma_f32 v[48:49], v[48:49], v[158:159], v[56:57] op_sel_hi:[1,0,1]
	v_pk_fma_f32 v[46:47], v[46:47], v[158:159], v[54:55] op_sel_hi:[1,0,1]
	v_pk_fma_f32 v[120:121], v[120:121], v[156:157], v[40:41] op_sel_hi:[1,0,1]
	v_pk_fma_f32 v[118:119], v[118:119], v[156:157], v[38:39] op_sel_hi:[1,0,1]
	v_pk_fma_f32 v[36:37], v[36:37], v[158:159], v[40:41] op_sel_hi:[1,0,1]
	v_pk_fma_f32 v[34:35], v[34:35], v[158:159], v[38:39] op_sel_hi:[1,0,1]
	v_pk_fma_f32 v[44:45], v[44:45], v[160:161], v[40:41] op_sel_hi:[1,0,1]
	v_pk_fma_f32 v[42:43], v[42:43], v[160:161], v[38:39] op_sel_hi:[1,0,1]
	v_cmp_ne_u32_e64 s[10:11], 1, v154
	s_and_saveexec_b64 s[12:13], s[2:3]
	s_cbranch_execz .LBB0_1333
	s_and_b64 vcc, exec, s[10:11]
	ds_write_b128 v210, v[142:145]
	ds_write_b128 v210, v[138:141] offset:16
	ds_write_b128 v210, v[130:133] offset:512
	ds_write_b128 v210, v[122:125] offset:528
	ds_write_b128 v210, v[146:149] offset:1024
	ds_write_b128 v210, v[134:137] offset:1040
	ds_write_b128 v210, v[126:129] offset:1536
	ds_write_b128 v210, v[118:121] offset:1552
	ds_write_b128 v210, v[74:77] offset:4096
	ds_write_b128 v210, v[58:61] offset:4112
	ds_write_b128 v210, v[46:49] offset:4608
	ds_write_b128 v210, v[34:37] offset:4624
	ds_write_b128 v210, v[78:81] offset:5120
	ds_write_b128 v210, v[62:65] offset:5136
	ds_write_b128 v210, v[50:53] offset:5632
	ds_write_b128 v210, v[42:45] offset:5648
	s_cbranch_vccnz .LBB0_1333
	s_mul_i32 s40, s94, 0x2b000
	s_mul_hi_i32 s19, s94, 0x2b000
	s_add_u32 s40, s50, s40
	s_addc_u32 s41, s48, s19
	v_lshlrev_b32_e32 v154, 2, v200
	s_add_u32 s100, s40, 0x15000
	s_addc_u32 s101, s41, 0
	global_store_dwordx4 v154, v[74:77], s[100:101] offset:2048
	global_store_dwordx4 v154, v[58:61], s[100:101] offset:2064
	s_add_u32 s100, s40, 0x1a000
	s_addc_u32 s101, s41, 0
	global_store_dwordx4 v154, v[46:49], s[100:101] offset:3584
	global_store_dwordx4 v154, v[34:37], s[100:101] offset:3600
	s_add_u32 s100, s40, 0x20000
	s_addc_u32 s101, s41, 0
	global_store_dwordx4 v154, v[78:81], s[100:101] offset:1024
	global_store_dwordx4 v154, v[62:65], s[100:101] offset:1040
	s_add_u32 s100, s40, 0x25000
	s_addc_u32 s101, s41, 0
	global_store_dwordx4 v154, v[50:53], s[100:101] offset:2560
	global_store_dwordx4 v154, v[42:45], s[100:101] offset:2576
; #define PG8_LAS __attribute__((address_space(3)))
;     template <bool PR = false> __device__ __forceinline__ void apply(f32x4 (&acc)[2][2][4][2], int p, int wr, int wc, int fr, int fq) const {
;     ...
;             for (int m = 0; m < 4; ++m) rs[ai][m] = __builtin_amdgcn_rsqf((float)Tr[ai * HALF + (PR ? m : m * 16)] * (1.0f / (1048576.0f * 2048.0f)) + 1e-6f);
; #pragma unroll
;         for (int bj = 0; bj < 2; ++bj)
; #pragma unroll
;             for (int n = 0; n < 2; ++n) { const f32x4 bv = *(const PG8_LAS f32x4*)(Tb + bj * HALF + 4 * n);
; #pragma unroll
;                 for (int ai = 0; ai < 2; ++ai)
; #pragma unroll
;                     for (int m = 0; m < 4; ++m) acc[ai][bj][m][n] = acc[ai][bj][m][n] * rs[ai][m] + bv; }
;     __device__ __forceinline__ void operator()(f32x4 (&acc)[2][2][4][2], const Unit& u, int p, int wr, int wc, int fr, int fq) const {
;     ...
;         if (fr == 0 && wr == 0) {
; #pragma unroll
;             for (int mm = 0; mm < 2; ++mm)
; #pragma unroll
;                 for (int bj = 0; bj < 2; ++bj)
; #pragma unroll
;                     for (int n = 0; n < 2; ++n) *(f32x4*)(HALO + ((size_t)u.pm * 4 + mm) * 11008 + bj * 5504 + ch0 + 4 * n) = acc[0][bj][mm][n]; }
.LBB0_1333:
	s_or_b64 exec, exec, s[12:13]
	v_ashrrev_i32_e32 v201, 31, v200
	s_and_saveexec_b64 s[12:13], s[4:5]
	s_xor_b64 s[12:13], exec, s[12:13]
	s_or_saveexec_b64 s[12:13], s[12:13]
	v_ffbh_u32_e32 v154, v151
	v_min_u32_e32 v154, 32, v154
	v_lshlrev_b64 v[150:151], v154, v[150:151]
	v_min_u32_e32 v150, 1, v150
	v_or_b32_e32 v150, v151, v150
	v_cvt_f32_u32_e32 v150, v150
	v_ffbh_u32_e32 v151, v153
	v_min_u32_e32 v155, 32, v151
	v_sub_u32_e32 v151, 32, v154
	v_ldexp_f32 v154, v150, v151
	v_lshlrev_b64 v[150:151], v155, v[152:153]
	v_min_u32_e32 v150, 1, v150
	v_or_b32_e32 v150, v151, v150
	v_cvt_f32_u32_e32 v150, v150
	v_fmamk_f32 v151, v154, 0x30000000, v233
	v_rsq_f32_e32 v170, v151
	v_sub_u32_e32 v151, 32, v155
	v_ldexp_f32 v150, v150, v151
	v_fmamk_f32 v150, v150, 0x30000000, v233
	v_rsq_f32_e32 v172, v150
	v_pk_fma_f32 v[164:165], v[116:117], v[170:171], v[84:85] op_sel_hi:[1,0,1]
	v_pk_fma_f32 v[162:163], v[114:115], v[170:171], v[82:83] op_sel_hi:[1,0,1]
	v_pk_fma_f32 v[156:157], v[100:101], v[170:171], v[56:57] op_sel_hi:[1,0,1]
	v_pk_fma_f32 v[168:169], v[112:113], v[172:173], v[84:85] op_sel_hi:[1,0,1]
	v_pk_fma_f32 v[166:167], v[110:111], v[172:173], v[82:83] op_sel_hi:[1,0,1]
	v_pk_fma_f32 v[112:113], v[108:109], v[170:171], v[68:69] op_sel_hi:[1,0,1]
	v_pk_fma_f32 v[110:111], v[106:107], v[170:171], v[66:67] op_sel_hi:[1,0,1]
	v_pk_fma_f32 v[160:161], v[104:105], v[172:173], v[68:69] op_sel_hi:[1,0,1]
	v_pk_fma_f32 v[158:159], v[102:103], v[172:173], v[66:67] op_sel_hi:[1,0,1]
	v_pk_fma_f32 v[154:155], v[98:99], v[170:171], v[54:55] op_sel_hi:[1,0,1]
	v_pk_fma_f32 v[152:153], v[96:97], v[172:173], v[56:57] op_sel_hi:[1,0,1]
	v_pk_fma_f32 v[150:151], v[94:95], v[172:173], v[54:55] op_sel_hi:[1,0,1]
	v_pk_fma_f32 v[104:105], v[92:93], v[170:171], v[40:41] op_sel_hi:[1,0,1]
	v_pk_fma_f32 v[102:103], v[90:91], v[170:171], v[38:39] op_sel_hi:[1,0,1]
	v_pk_fma_f32 v[100:101], v[88:89], v[172:173], v[40:41] op_sel_hi:[1,0,1]
	v_pk_fma_f32 v[98:99], v[86:87], v[172:173], v[38:39] op_sel_hi:[1,0,1]
	s_xor_b64 exec, exec, s[12:13]
	s_cbranch_execz .LBB0_1335
	s_mul_i32 s40, s94, 0x2b000
	s_mul_hi_i32 s19, s94, 0x2b000
	s_add_u32 s40, s50, s40
	s_addc_u32 s41, s48, s19
	v_lshlrev_b32_e32 v86, 2, v200
	global_store_dwordx4 v86, v[162:165], s[40:41]
	global_store_dwordx4 v86, v[110:113], s[40:41] offset:16
	s_add_u32 s100, s40, 0x5000
	s_addc_u32 s101, s41, 0
	global_store_dwordx4 v86, v[154:157], s[100:101] offset:1536
	global_store_dwordx4 v86, v[102:105], s[100:101] offset:1552
	s_add_u32 s100, s40, 0xa000
	s_addc_u32 s101, s41, 0
	global_store_dwordx4 v86, v[166:169], s[100:101] offset:3072
	s_add_u32 s100, s40, 0xac00
	s_addc_u32 s101, s41, 0
	global_store_dwordx4 v86, v[158:161], s[100:101] offset:16
	s_add_u32 s100, s40, 0x10000
	s_addc_u32 s101, s41, 0
	global_store_dwordx4 v86, v[150:153], s[100:101] offset:512
	global_store_dwordx4 v86, v[98:101], s[100:101] offset:528
